# NA-latent tile loop: K and V fragment LDS reads hoisted into free VGPRs, QK MFMAs of the two key halves interleaved
# speedup vs baseline: 1.0059x; 1.0059x over previous
.LBB0_353:
	s_bitcmp1_b32 s66, 0
	s_cselect_b32 s68, 0x4800, 0
	v_or_b32_e32 v34, s68, v100
	v_add_u32_e32 v119, v34, v112
	ds_read_b128 v[168:171], v119
	ds_read_b128 v[184:187], v119 offset:4608
	ds_read_b128 v[172:175], v119 offset:32
	ds_read_b128 v[188:191], v119 offset:4640
	ds_read_b128 v[176:179], v119 offset:64
	ds_read_b128 v[192:195], v119 offset:4672
	ds_read_b128 v[180:183], v119 offset:96
	ds_read_b128 v[196:199], v119 offset:4704
	s_add_i32 s40, s61, s66
	v_cmp_lt_i32_e32 vcc, s40, v114
	s_cmp_gt_u32 s66, 3
	v_cmp_ge_i32_e64 s[40:41], s40, v113
	s_cselect_b64 s[64:65], -1, 0
	s_and_b64 s[62:63], s[40:41], vcc
	s_cmp_lt_u32 s66, 4
	s_waitcnt lgkmcnt(7)
	v_mfma_f32_32x32x16_bf16 v[50:65], v[168:171], v[66:69], 0
	s_waitcnt lgkmcnt(6)
	v_mfma_f32_32x32x16_bf16 v[34:49], v[184:187], v[66:69], 0
	s_waitcnt lgkmcnt(5)
	v_mfma_f32_32x32x16_bf16 v[50:65], v[172:175], v[70:73], v[50:65]
	s_waitcnt lgkmcnt(4)
	v_mfma_f32_32x32x16_bf16 v[34:49], v[188:191], v[70:73], v[34:49]
	s_waitcnt lgkmcnt(3)
	v_mfma_f32_32x32x16_bf16 v[50:65], v[176:179], v[74:77], v[50:65]
	s_waitcnt lgkmcnt(2)
	v_mfma_f32_32x32x16_bf16 v[34:49], v[192:195], v[74:77], v[34:49]
	s_waitcnt lgkmcnt(1)
	v_mfma_f32_32x32x16_bf16 v[50:65], v[180:183], v[78:81], v[50:65]
	s_waitcnt lgkmcnt(0)
	v_mfma_f32_32x32x16_bf16 v[34:49], v[196:199], v[78:81], v[34:49]
	v_add3_u32 v208, s68, v101, v112
	v_add_u32_e32 v209, 0x3000, v208
	v_add_u32_e32 v208, 0x2000, v208
	ds_read2_b64 v[200:203], v208 offset0:128 offset1:130
	ds_read2_b64 v[204:207], v208 offset0:132 offset1:134
	ds_read2_b64 v[234:237], v209 offset0:192 offset1:194
	ds_read2_b64 v[238:241], v209 offset0:196 offset1:198
	ds_read2_b64 v[242:245], v208 offset0:136 offset1:138
	ds_read2_b64 v[246:249], v209 offset0:200 offset1:202
	ds_read2_b64 v[214:217], v208 offset0:140 offset1:142
	ds_read2_b64 v[228:231], v209 offset0:204 offset1:206
	s_nop 0
	v_mul_f32_e32 v50, 0x3e38aa3b, v50
	s_cbranch_scc1 .LBB0_355
	v_readlane_b32 s40, v255, 19
	v_readlane_b32 s41, v255, 20
	s_and_b64 vcc, s[62:63], s[40:41]
	v_cndmask_b32_e32 v133, v166, v116, vcc
	v_lshlrev_b32_e32 v133, 2, v133
	ds_read_b32 v133, v133 offset:36864

.LBB0_389:
	v_sub_f32_e32 v50, v50, v35
	v_exp_f32_e32 v50, v50
	v_sub_f32_e32 v51, v51, v35
	v_exp_f32_e32 v51, v51
	v_sub_f32_e32 v52, v52, v35
	v_exp_f32_e32 v52, v52
	v_sub_f32_e32 v53, v53, v35
	v_exp_f32_e32 v53, v53
	v_sub_f32_e32 v54, v54, v35
	v_add_f32_e32 v118, 0, v50
	v_exp_f32_e32 v54, v54
	v_sub_f32_e32 v55, v55, v35
	v_add_f32_e32 v118, v51, v118
	v_exp_f32_e32 v55, v55
	v_sub_f32_e32 v56, v56, v35
	v_add_f32_e32 v118, v52, v118
	v_exp_f32_e32 v56, v56
	v_sub_f32_e32 v57, v57, v35
	v_add_f32_e32 v118, v53, v118
	v_exp_f32_e32 v57, v57
	v_sub_f32_e32 v58, v58, v35
	v_add_f32_e32 v118, v54, v118
	v_exp_f32_e32 v58, v58
	v_sub_f32_e32 v59, v59, v35
	v_add_f32_e32 v118, v55, v118
	v_exp_f32_e32 v59, v59
	v_sub_f32_e32 v60, v60, v35
	v_add_f32_e32 v118, v56, v118
	v_exp_f32_e32 v60, v60
	v_sub_f32_e32 v61, v61, v35
	v_add_f32_e32 v118, v57, v118
	v_exp_f32_e32 v61, v61
	v_sub_f32_e32 v62, v62, v35
	v_add_f32_e32 v118, v58, v118
	v_exp_f32_e32 v62, v62
	v_sub_f32_e32 v63, v63, v35
	v_add_f32_e32 v118, v59, v118
	v_exp_f32_e32 v63, v63
	v_sub_f32_e32 v64, v64, v35
	v_add_f32_e32 v118, v60, v118
	v_exp_f32_e32 v64, v64
	v_sub_f32_e32 v65, v65, v35
	v_add_f32_e32 v118, v61, v118
	v_exp_f32_e32 v65, v65
	v_sub_f32_e32 v119, v119, v35
	v_add_f32_e32 v118, v62, v118
	v_exp_f32_e32 v119, v119
	v_sub_f32_e32 v120, v120, v35
	v_add_f32_e32 v118, v63, v118
	v_exp_f32_e32 v120, v120
	v_sub_f32_e32 v36, v36, v35
	v_add_f32_e32 v118, v64, v118
	v_exp_f32_e32 v121, v36
	v_add_f32_e32 v118, v65, v118
	v_add_f32_e32 v118, v119, v118
	v_sub_f32_e32 v37, v37, v35
	v_add_f32_e32 v118, v120, v118
	v_exp_f32_e32 v37, v37
	v_sub_f32_e32 v38, v38, v35
	v_add_f32_e32 v36, v121, v118
	v_exp_f32_e32 v118, v38
	v_sub_f32_e32 v38, v39, v35
	v_exp_f32_e32 v122, v38
	v_sub_f32_e32 v38, v40, v35
	v_exp_f32_e32 v123, v38
	v_sub_f32_e32 v38, v41, v35
	v_add_f32_e32 v36, v37, v36
	v_exp_f32_e32 v124, v38
	v_sub_f32_e32 v38, v42, v35
	v_add_f32_e32 v36, v118, v36
	v_exp_f32_e32 v125, v38
	v_sub_f32_e32 v38, v43, v35
	v_add_f32_e32 v36, v122, v36
	v_exp_f32_e32 v126, v38
	v_sub_f32_e32 v38, v44, v35
	v_add_f32_e32 v36, v123, v36
	v_exp_f32_e32 v127, v38
	v_sub_f32_e32 v38, v45, v35
	v_add_f32_e32 v36, v124, v36
	v_exp_f32_e32 v128, v38
	v_sub_f32_e32 v38, v46, v35
	v_add_f32_e32 v36, v125, v36
	v_exp_f32_e32 v129, v38
	v_sub_f32_e32 v38, v47, v35
	v_add_f32_e32 v36, v126, v36
	v_exp_f32_e32 v130, v38
	v_sub_f32_e32 v38, v48, v35
	v_add_f32_e32 v36, v127, v36
	v_exp_f32_e32 v131, v38
	v_sub_f32_e32 v38, v49, v35
	v_add_f32_e32 v36, v128, v36
	v_exp_f32_e32 v132, v38
	v_add_f32_e32 v36, v129, v36
	v_add_f32_e32 v36, v130, v36
	v_add_f32_e32 v36, v131, v36
	v_add_f32_e32 v36, v132, v36
	v_fmac_f32_e32 v36, v117, v34
	v_add3_u32 v34, s68, v101, v112
	v_cvt_pk_bf16_f32 v38, v50, v51
	v_add_u32_e32 v50, 0x2000, v34
	v_cvt_pk_bf16_f32 v39, v52, v53
	v_cvt_pk_bf16_f32 v40, v54, v55
	v_cvt_pk_bf16_f32 v41, v56, v57
	v_add_u32_e32 v34, 0x3000, v34
	s_add_u32 s46, s46, 0x80
	s_waitcnt lgkmcnt(1)
	v_mfma_f32_32x32x16_bf16 v[18:33], v[200:203], v[38:41], v[18:33]
	s_addc_u32 s47, s47, 0
	s_add_u32 s48, s48, 0x2000
	s_addc_u32 s49, s49, 0
	v_add_u32_e32 v116, 31, v116
	s_andn2_b64 vcc, exec, s[44:45]
	s_waitcnt lgkmcnt(0)
	v_mfma_f32_32x32x16_bf16 v[2:17], v[234:237], v[38:41], v[2:17]
	v_cvt_pk_bf16_f32 v38, v58, v59
	v_cvt_pk_bf16_f32 v39, v60, v61
	v_cvt_pk_bf16_f32 v40, v62, v63
	v_cvt_pk_bf16_f32 v41, v64, v65
	s_waitcnt lgkmcnt(0)
	s_nop 0
	v_mfma_f32_32x32x16_bf16 v[2:17], v[238:241], v[38:41], v[2:17]
	v_mfma_f32_32x32x16_bf16 v[18:33], v[204:207], v[38:41], v[18:33]
	v_cvt_pk_bf16_f32 v38, v119, v120
	v_cvt_pk_bf16_f32 v39, v121, v37
	v_cvt_pk_bf16_f32 v40, v118, v122
	v_cvt_pk_bf16_f32 v41, v123, v124
	s_waitcnt lgkmcnt(0)
	s_nop 0
	v_mfma_f32_32x32x16_bf16 v[18:33], v[242:245], v[38:41], v[18:33]
	s_waitcnt lgkmcnt(0)
	v_mfma_f32_32x32x16_bf16 v[2:17], v[246:249], v[38:41], v[2:17]
	v_cvt_pk_bf16_f32 v38, v125, v126
	v_cvt_pk_bf16_f32 v39, v127, v128
	v_cvt_pk_bf16_f32 v40, v129, v130
	v_cvt_pk_bf16_f32 v41, v131, v132
	s_waitcnt lgkmcnt(0)
	s_nop 0
	v_mfma_f32_32x32x16_bf16 v[18:33], v[214:217], v[38:41], v[18:33]
	s_waitcnt lgkmcnt(0)
	s_barrier
	v_mfma_f32_32x32x16_bf16 v[2:17], v[228:231], v[38:41], v[2:17]
	s_cbranch_vccz .LBB0_421
	v_mov_b32_e32 v117, v36
	s_mov_b32 s66, s70
	v_mov_b32_e32 v118, v35
	s_branch .LBB0_347
